# attn PV V-fragment reads issued 4 ahead of MFMAs; samp_b T5-bias loads hoisted out of the score loop (no in-loop vmcnt(0))
# speedup vs baseline: 1.0022x; 1.0022x over previous
.LBB0_470:
	s_or_b64 exec, exec, s[20:21]
	s_waitcnt vmcnt(0)
	v_mov_b32_e32 v12, v96
	v_mov_b32_e32 v11, v95
	s_and_saveexec_b64 s[20:21], s[16:17]
	v_mov_b32_e32 v12, v97
	v_mov_b32_e32 v97, v94
	v_mov_b32_e32 v11, v96
	v_mov_b32_e32 v94, v95
	s_or_b64 exec, exec, s[20:21]
	v_mov_b32_e32 v14, v12
	v_mov_b32_e32 v13, v97
	s_and_saveexec_b64 s[20:21], s[18:19]
	v_mov_b32_e32 v14, v94
	v_mov_b32_e32 v13, v11
	v_mov_b32_e32 v11, v97
	v_mov_b32_e32 v94, v12
	s_or_b64 exec, exec, s[20:21]
	v_add_u32_e32 v12, v153, v154
	ds_write_b16 v12, v94
	v_add_u32_e32 v12, v153, v155
	ds_write_b16_d16_hi v12, v94
	v_add_u32_e32 v12, v153, v156
	ds_write_b16 v12, v11
	v_add_u32_e32 v12, v153, v157
	ds_write_b16_d16_hi v12, v11
	v_add_u32_e32 v11, v153, v158
	ds_write_b16 v11, v14
	v_add_u32_e32 v11, v153, v159
	ds_write_b16_d16_hi v11, v14
	v_add_u32_e32 v11, v153, v160
	ds_write_b16 v11, v13
	v_add_u32_e32 v11, v153, v161
	ds_write_b16_d16_hi v11, v13
	s_and_saveexec_b64 s[20:21], s[14:15]
	s_mov_b32 s23, 0x1000706
	v_perm_b32 v11, v86, v87, s23
	v_perm_b32 v87, v87, v88, s23
	v_perm_b32 v88, v88, v89, s23
	v_perm_b32 v89, v89, v86, s23
	v_mov_b32_e32 v86, v11
	s_or_b64 exec, exec, s[20:21]
	v_mov_b32_e32 v12, v88
	v_mov_b32_e32 v11, v87
	s_and_saveexec_b64 s[20:21], s[16:17]
	v_mov_b32_e32 v12, v89
	v_mov_b32_e32 v89, v86
	v_mov_b32_e32 v11, v88
	v_mov_b32_e32 v86, v87
	s_or_b64 exec, exec, s[20:21]
	v_mov_b32_e32 v14, v12
	v_mov_b32_e32 v13, v89
	s_and_saveexec_b64 s[20:21], s[18:19]
	v_mov_b32_e32 v14, v86
	v_mov_b32_e32 v13, v11
	v_mov_b32_e32 v11, v89
	v_mov_b32_e32 v86, v12
	s_or_b64 exec, exec, s[20:21]
	v_add_u32_e32 v12, v162, v154
	ds_write_b16 v12, v86
	v_add_u32_e32 v12, v162, v155
	ds_write_b16_d16_hi v12, v86
	v_add_u32_e32 v12, v162, v156
	ds_write_b16 v12, v11
	v_add_u32_e32 v12, v162, v157
	ds_write_b16_d16_hi v12, v11
	v_add_u32_e32 v11, v162, v158
	ds_write_b16 v11, v14
	v_add_u32_e32 v11, v162, v159
	ds_write_b16_d16_hi v11, v14
	v_add_u32_e32 v11, v162, v160
	ds_write_b16 v11, v13
	v_add_u32_e32 v11, v162, v161
	ds_write_b16_d16_hi v11, v13
	s_and_saveexec_b64 s[20:21], s[14:15]
	s_mov_b32 s23, 0x1000706
	v_perm_b32 v11, v90, v91, s23
	v_perm_b32 v91, v91, v92, s23
	v_perm_b32 v92, v92, v93, s23
	v_perm_b32 v93, v93, v90, s23
	v_mov_b32_e32 v90, v11
	s_or_b64 exec, exec, s[20:21]
	v_mov_b32_e32 v12, v92
	v_mov_b32_e32 v11, v91
	s_and_saveexec_b64 s[20:21], s[16:17]
	v_mov_b32_e32 v12, v93
	v_mov_b32_e32 v93, v90
	v_mov_b32_e32 v11, v92
	v_mov_b32_e32 v90, v91
	s_or_b64 exec, exec, s[20:21]
	v_mov_b32_e32 v14, v12
	v_mov_b32_e32 v13, v93
	s_and_saveexec_b64 s[20:21], s[18:19]
	v_mov_b32_e32 v14, v90
	v_mov_b32_e32 v13, v11
	v_mov_b32_e32 v11, v93
	v_mov_b32_e32 v90, v12
	s_or_b64 exec, exec, s[20:21]
	v_add_u32_e32 v12, v163, v154
	ds_write_b16 v12, v90
	v_add_u32_e32 v12, v163, v155
	ds_write_b16_d16_hi v12, v90
	v_add_u32_e32 v12, v163, v156
	ds_write_b16 v12, v11
	v_add_u32_e32 v12, v163, v157
	ds_write_b16_d16_hi v12, v11
	v_add_u32_e32 v11, v163, v158
	ds_write_b16 v11, v14
	v_add_u32_e32 v11, v163, v159
	ds_write_b16_d16_hi v11, v14
	v_add_u32_e32 v11, v163, v160
	ds_write_b16 v11, v13
	v_add_u32_e32 v11, v163, v161
	ds_write_b16_d16_hi v11, v13
	s_and_saveexec_b64 s[20:21], s[14:15]
	s_mov_b32 s23, 0x1000706
	v_perm_b32 v11, v82, v83, s23
	v_perm_b32 v83, v83, v84, s23
	v_perm_b32 v84, v84, v85, s23
	v_perm_b32 v85, v85, v82, s23
	v_mov_b32_e32 v82, v11
	s_or_b64 exec, exec, s[20:21]
	v_mov_b32_e32 v14, v84
	v_mov_b32_e32 v11, v83
	s_and_saveexec_b64 s[20:21], s[16:17]
	v_mov_b32_e32 v14, v85
	v_mov_b32_e32 v85, v82
	v_mov_b32_e32 v11, v84
	v_mov_b32_e32 v82, v83
	s_or_b64 exec, exec, s[20:21]
	v_mov_b32_e32 v13, v14
	v_mov_b32_e32 v12, v85
	s_and_saveexec_b64 s[20:21], s[18:19]
	v_mov_b32_e32 v13, v82
	v_mov_b32_e32 v12, v11
	v_mov_b32_e32 v11, v85
	v_mov_b32_e32 v82, v14
	s_or_b64 exec, exec, s[20:21]
	v_add_u32_e32 v14, v164, v154
	ds_write_b16 v14, v82
	v_add_u32_e32 v14, v164, v155
	ds_write_b16_d16_hi v14, v82
	v_add_u32_e32 v14, v164, v156
	ds_write_b16 v14, v11
	v_add_u32_e32 v14, v164, v157
	ds_write_b16_d16_hi v14, v11
	v_add_u32_e32 v11, v164, v158
	ds_write_b16 v11, v13
	v_add_u32_e32 v11, v164, v159
	ds_write_b16_d16_hi v11, v13
	v_add_u32_e32 v11, v164, v160
	ds_write_b16 v11, v12
	v_add_u32_e32 v11, v164, v161
	ds_write_b16_d16_hi v11, v12
	s_waitcnt lgkmcnt(0)
	s_barrier
	ds_read_b128 v[198:201], v127
	ds_read_b128 v[202:205], v127 offset:16896
	ds_read_b128 v[240:243], v127 offset:32
	ds_read_b128 v[216:219], v127 offset:16928
	v_sub_f32_e32 v0, v137, v0
	v_mul_f32_e32 v0, 0x3fb8aa3b, v0
	v_exp_f32_e32 v0, v0
	v_cvt_pk_bf16_f32 v2, v1, v2
	v_cvt_pk_bf16_f32 v3, v3, v4
	v_cvt_pk_bf16_f32 v4, v5, v6
	v_cvt_pk_bf16_f32 v5, v7, v8
	v_add_f32_e32 v1, v9, v10
	v_ashrrev_i32_e32 v139, 31, v138
	s_waitcnt lgkmcnt(3)
	v_mfma_f32_32x32x16_bf16 v[16:31], v[198:201], v[2:5], 0
	ds_read_b128 v[198:201], v129
	v_add_f32_e32 v90, v0, v1
	s_waitcnt lgkmcnt(3)
	v_mfma_f32_32x32x16_bf16 v[0:15], v[202:205], v[2:5], 0
	ds_read_b128 v[202:205], v129 offset:16896
	v_cvt_pk_bf16_f32 v86, v32, v33
	v_cvt_pk_bf16_f32 v87, v35, v37
	v_cvt_pk_bf16_f32 v88, v40, v45
	v_cvt_pk_bf16_f32 v89, v48, v109
	s_waitcnt lgkmcnt(3)
	s_nop 0
	v_mfma_f32_32x32x16_bf16 v[16:31], v[240:243], v[86:89], v[16:31]
	ds_read_b128 v[240:243], v129 offset:32
	s_waitcnt lgkmcnt(3)
	v_mfma_f32_32x32x16_bf16 v[0:15], v[216:219], v[86:89], v[0:15]
	ds_read_b128 v[216:219], v129 offset:16928
	v_cvt_pk_bf16_f32 v86, v42, v49
	v_cvt_pk_bf16_f32 v87, v54, v61
	v_cvt_pk_bf16_f32 v88, v67, v74
	v_cvt_pk_bf16_f32 v89, v79, v104
	s_waitcnt lgkmcnt(3)
	s_nop 0
	v_mfma_f32_32x32x16_bf16 v[16:31], v[198:201], v[86:89], v[16:31]
	ds_read_b128 v[198:201], v165
	s_waitcnt lgkmcnt(3)
	v_mfma_f32_32x32x16_bf16 v[0:15], v[202:205], v[86:89], v[0:15]
	ds_read_b128 v[202:205], v165 offset:16896
	v_cvt_pk_bf16_f32 v32, v34, v36
	v_cvt_pk_bf16_f32 v33, v39, v43
	v_cvt_pk_bf16_f32 v34, v47, v55
	v_cvt_pk_bf16_f32 v35, v58, v114
	s_waitcnt lgkmcnt(3)
	s_nop 0
	v_mfma_f32_32x32x16_bf16 v[16:31], v[240:243], v[32:35], v[16:31]
	ds_read_b128 v[240:243], v165 offset:32
	s_waitcnt lgkmcnt(3)
	v_mfma_f32_32x32x16_bf16 v[0:15], v[216:219], v[32:35], v[0:15]
	ds_read_b128 v[216:219], v165 offset:16928
	v_cvt_pk_bf16_f32 v82, v51, v59
	v_cvt_pk_bf16_f32 v83, v64, v71
	v_cvt_pk_bf16_f32 v84, v77, v101
	v_cvt_pk_bf16_f32 v85, v106, v111
	s_waitcnt lgkmcnt(3)
	s_nop 0
	v_mfma_f32_32x32x16_bf16 v[16:31], v[198:201], v[82:85], v[16:31]
	ds_read_b128 v[198:201], v166
	s_waitcnt lgkmcnt(3)
	v_mfma_f32_32x32x16_bf16 v[0:15], v[202:205], v[82:85], v[0:15]
	ds_read_b128 v[202:205], v166 offset:16896
	v_cvt_pk_bf16_f32 v36, v38, v41
	v_cvt_pk_bf16_f32 v37, v46, v52
	v_cvt_pk_bf16_f32 v38, v57, v65
	v_cvt_pk_bf16_f32 v39, v69, v118
	s_waitcnt lgkmcnt(3)
	s_nop 0
	v_mfma_f32_32x32x16_bf16 v[16:31], v[240:243], v[36:39], v[16:31]
	ds_read_b128 v[240:243], v166 offset:32
	s_waitcnt lgkmcnt(3)
	v_mfma_f32_32x32x16_bf16 v[0:15], v[216:219], v[36:39], v[0:15]
	ds_read_b128 v[216:219], v166 offset:16928
	v_cvt_pk_bf16_f32 v36, v62, v70
	v_cvt_pk_bf16_f32 v37, v75, v100
	v_cvt_pk_bf16_f32 v38, v105, v110
	v_cvt_pk_bf16_f32 v39, v113, v116
	s_waitcnt lgkmcnt(3)
	s_nop 0
	v_mfma_f32_32x32x16_bf16 v[16:31], v[198:201], v[36:39], v[16:31]
	ds_read_b128 v[198:201], v127 offset:256
	s_waitcnt lgkmcnt(3)
	v_mfma_f32_32x32x16_bf16 v[0:15], v[202:205], v[36:39], v[0:15]
	ds_read_b128 v[202:205], v127 offset:17152
	v_cvt_pk_bf16_f32 v36, v44, v50
	v_cvt_pk_bf16_f32 v37, v56, v63
	v_cvt_pk_bf16_f32 v38, v68, v76
	v_cvt_pk_bf16_f32 v39, v98, v120
	s_waitcnt lgkmcnt(3)
	s_nop 0
	v_mfma_f32_32x32x16_bf16 v[16:31], v[240:243], v[36:39], v[16:31]
	ds_read_b128 v[240:243], v127 offset:288
	s_waitcnt lgkmcnt(3)
	v_mfma_f32_32x32x16_bf16 v[0:15], v[216:219], v[36:39], v[0:15]
	ds_read_b128 v[216:219], v127 offset:17184
	v_cvt_pk_bf16_f32 v36, v72, v99
	v_cvt_pk_bf16_f32 v37, v102, v108
	v_cvt_pk_bf16_f32 v38, v112, v115
	v_cvt_pk_bf16_f32 v39, v117, v119
	s_waitcnt lgkmcnt(3)
	s_nop 0
	v_mfma_f32_32x32x16_bf16 v[16:31], v[198:201], v[36:39], v[16:31]
	s_waitcnt lgkmcnt(2)
	v_mfma_f32_32x32x16_bf16 v[0:15], v[202:205], v[36:39], v[0:15]
	v_cvt_pk_bf16_f32 v36, v53, v60
	v_cvt_pk_bf16_f32 v37, v66, v73
	v_cvt_pk_bf16_f32 v38, v78, v103
	v_cvt_pk_bf16_f32 v39, v107, v121
	s_waitcnt lgkmcnt(1)
	s_nop 0
	v_mfma_f32_32x32x16_bf16 v[16:31], v[240:243], v[36:39], v[16:31]
	s_waitcnt lgkmcnt(0)
	v_mfma_f32_32x32x16_bf16 v[0:15], v[216:219], v[36:39], v[0:15]
	v_div_scale_f32 v32, s[20:21], v90, v90, 1.0
	v_rcp_f32_e32 v33, v32
	v_div_scale_f32 v34, vcc, 1.0, v90, 1.0
	v_mov_b32_e32 v137, v209
	v_fma_f32 v35, -v32, v33, 1.0
	v_fmac_f32_e32 v33, v35, v33
	v_mul_f32_e32 v35, v34, v33
	v_fma_f32 v36, -v32, v35, v34
	v_fmac_f32_e32 v35, v36, v33
	v_fma_f32 v32, -v32, v35, v34
	v_div_fmas_f32 v32, v32, v33, v35
	v_lshlrev_b64 v[34:35], 11, v[138:139]
	v_lshl_add_u64 v[34:35], s[26:27], 0, v[34:35]
	v_lshl_add_u64 v[34:35], s[40:41], 1, v[34:35]
	v_div_fixup_f32 v32, v32, v90, 1.0
	v_lshl_add_u64 v[34:35], v[34:35], 0, v[136:137]
	s_mov_b64 s[20:21], 0xbe00600
	v_lshl_add_u64 v[36:37], v[34:35], 0, s[20:21]
	v_pk_mul_f32 v[0:1], v[32:33], v[0:1] op_sel_hi:[0,1]
	v_pk_mul_f32 v[2:3], v[32:33], v[2:3] op_sel_hi:[0,1]
	s_mov_b32 s20, 0xbe00000
	v_pk_mul_f32 v[16:17], v[32:33], v[16:17] op_sel_hi:[0,1]
	v_pk_mul_f32 v[18:19], v[32:33], v[18:19] op_sel_hi:[0,1]
	v_cvt_pk_bf16_f32 v0, v0, v1
	v_cvt_pk_bf16_f32 v1, v2, v3
	v_add_co_u32_e32 v2, vcc, s20, v34
	v_cvt_pk_bf16_f32 v16, v16, v17
	v_cvt_pk_bf16_f32 v17, v18, v19
	v_addc_co_u32_e32 v3, vcc, 0, v35, vcc
	global_store_dwordx2 v[2:3], v[16:17], off offset:1536
	global_store_dwordx2 v[36:37], v[0:1], off offset:64
	v_pk_mul_f32 v[0:1], v[32:33], v[20:21] op_sel_hi:[0,1]
	v_pk_mul_f32 v[2:3], v[32:33], v[22:23] op_sel_hi:[0,1]
	v_cvt_pk_bf16_f32 v0, v0, v1
	v_cvt_pk_bf16_f32 v1, v2, v3
	v_pk_mul_f32 v[2:3], v[32:33], v[4:5] op_sel_hi:[0,1]
	v_pk_mul_f32 v[4:5], v[32:33], v[6:7] op_sel_hi:[0,1]
	v_cvt_pk_bf16_f32 v2, v2, v3
	v_cvt_pk_bf16_f32 v3, v4, v5
	global_store_dwordx2 v[36:37], v[0:1], off offset:16
	global_store_dwordx2 v[36:37], v[2:3], off offset:80
	v_pk_mul_f32 v[0:1], v[32:33], v[24:25] op_sel_hi:[0,1]
	v_pk_mul_f32 v[2:3], v[32:33], v[26:27] op_sel_hi:[0,1]
	v_cvt_pk_bf16_f32 v0, v0, v1
	v_cvt_pk_bf16_f32 v1, v2, v3
	v_pk_mul_f32 v[2:3], v[32:33], v[8:9] op_sel_hi:[0,1]
	v_pk_mul_f32 v[4:5], v[32:33], v[10:11] op_sel_hi:[0,1]
	v_cvt_pk_bf16_f32 v2, v2, v3
	v_cvt_pk_bf16_f32 v3, v4, v5
	global_store_dwordx2 v[36:37], v[0:1], off offset:32
	global_store_dwordx2 v[36:37], v[2:3], off offset:96
	v_pk_mul_f32 v[0:1], v[32:33], v[28:29] op_sel_hi:[0,1]
	v_pk_mul_f32 v[2:3], v[32:33], v[30:31] op_sel_hi:[0,1]
	v_cvt_pk_bf16_f32 v0, v0, v1
	v_cvt_pk_bf16_f32 v1, v2, v3
	v_pk_mul_f32 v[2:3], v[32:33], v[12:13] op_sel_hi:[0,1]
	v_pk_mul_f32 v[4:5], v[32:33], v[14:15] op_sel_hi:[0,1]
	v_cvt_pk_bf16_f32 v2, v2, v3
	v_cvt_pk_bf16_f32 v3, v4, v5
	s_cmp_lg_u32 s51, 31
	global_store_dwordx2 v[36:37], v[0:1], off offset:48
	global_store_dwordx2 v[36:37], v[2:3], off offset:112
	s_cbranch_scc1 .LBB0_419
	s_or_b32 s36, s50, 0xf80
	s_mov_b32 s23, s55
	v_lshl_add_u64 v[8:9], v[130:131], 0, s[22:23]
	v_add_u32_e32 v0, s36, v126
	s_movk_i32 s22, 0x1800
	v_mad_i64_i32 v[0:1], s[20:21], v0, s22, v[8:9]
	v_add_co_u32_e32 v4, vcc, 0x1000, v0
	v_add_u32_e32 v10, s36, v128
	s_nop 0
	v_addc_co_u32_e32 v5, vcc, 0, v1, vcc
	v_mad_i64_i32 v[8:9], s[20:21], v10, s22, v[8:9]
	v_add_co_u32_e32 v12, vcc, 0x1000, v8
	global_load_dwordx4 v[0:3], v[4:5], off offset:1536
	s_nop 0
	global_load_dwordx4 v[4:7], v[4:5], off offset:1792
	v_addc_co_u32_e32 v13, vcc, 0, v9, vcc
	global_load_dwordx4 v[8:11], v[12:13], off offset:1536
	s_nop 0
	global_load_dwordx4 v[12:15], v[12:13], off offset:1792
	v_readlane_b32 s20, v252, 11
	s_add_i32 s20, s49, s20
	s_ashr_i32 s21, s20, 31
	s_lshl_b64 s[20:21], s[20:21], 14
	s_or_b64 s[20:21], s[20:21], s[54:55]
	v_lshl_add_u64 v[24:25], s[20:21], 0, v[132:133]
	v_lshlrev_b64 v[24:25], 2, v[24:25]
	s_waitcnt vmcnt(3)
	v_lshlrev_b32_e32 v16, 16, v0
	v_and_b32_e32 v17, 0xffff0000, v0
	v_lshlrev_b32_e32 v18, 16, v1
	v_and_b32_e32 v19, 0xffff0000, v1
	v_lshl_add_u64 v[0:1], s[38:39], 0, v[24:25]
	global_store_dwordx4 v[0:1], v[16:19], off
	s_mov_b32 s22, 0x8bbc000
	s_waitcnt vmcnt(3)
	v_lshlrev_b32_e32 v20, 16, v4
	v_lshl_add_u64 v[16:17], s[28:29], 0, v[24:25]
	v_and_b32_e32 v21, 0xffff0000, v4
	v_lshlrev_b32_e32 v22, 16, v5
	v_and_b32_e32 v23, 0xffff0000, v5
	v_lshl_add_u64 v[0:1], s[0:1], 0, v[24:25]
	v_add_co_u32_e32 v18, vcc, s22, v16
	global_store_dwordx4 v[0:1], v[20:23], off
	v_lshlrev_b32_e32 v0, 16, v2
	v_and_b32_e32 v1, 0xffff0000, v2
	v_lshlrev_b32_e32 v2, 16, v3
	v_and_b32_e32 v3, 0xffff0000, v3
	v_addc_co_u32_e32 v19, vcc, 0, v17, vcc
	s_mov_b32 s22, 0x9c3c000
	global_store_dwordx4 v[18:19], v[0:3], off offset:16
	v_lshlrev_b32_e32 v4, 16, v6
	v_and_b32_e32 v5, 0xffff0000, v6
	v_add_co_u32_e32 v0, vcc, s22, v16
	v_lshlrev_b32_e32 v6, 16, v7
	v_and_b32_e32 v7, 0xffff0000, v7
	v_addc_co_u32_e32 v1, vcc, 0, v17, vcc
	v_lshl_add_u64 v[16:17], s[20:21], 0, v[134:135]
	global_store_dwordx4 v[0:1], v[4:7], off offset:16
	s_waitcnt vmcnt(5)
	v_lshlrev_b32_e32 v0, 16, v8
	v_and_b32_e32 v1, 0xffff0000, v8
	v_lshlrev_b32_e32 v2, 16, v9
	v_and_b32_e32 v3, 0xffff0000, v9
	v_lshlrev_b64 v[8:9], 2, v[16:17]
	s_waitcnt vmcnt(4)
	v_lshlrev_b32_e32 v4, 16, v12
	v_and_b32_e32 v5, 0xffff0000, v12
	v_lshlrev_b32_e32 v6, 16, v13
	v_and_b32_e32 v7, 0xffff0000, v13
	v_lshl_add_u64 v[12:13], s[38:39], 0, v[8:9]
	global_store_dwordx4 v[12:13], v[0:3], off
	s_nop 1
	v_lshl_add_u64 v[0:1], s[0:1], 0, v[8:9]
	v_lshl_add_u64 v[8:9], s[28:29], 0, v[8:9]
	global_store_dwordx4 v[0:1], v[4:7], off
	v_lshlrev_b32_e32 v0, 16, v10
	v_and_b32_e32 v1, 0xffff0000, v10
	v_add_co_u32_e32 v10, vcc, 0x8bbc000, v8
	v_lshlrev_b32_e32 v2, 16, v11
	v_and_b32_e32 v3, 0xffff0000, v11
	v_addc_co_u32_e32 v11, vcc, 0, v9, vcc
	global_store_dwordx4 v[10:11], v[0:3], off offset:16
	v_lshlrev_b32_e32 v4, 16, v14
	v_and_b32_e32 v5, 0xffff0000, v14
	v_add_co_u32_e32 v0, vcc, 0x9c3c000, v8
	v_lshlrev_b32_e32 v6, 16, v15
	v_and_b32_e32 v7, 0xffff0000, v15
	v_addc_co_u32_e32 v1, vcc, 0, v9, vcc
	global_store_dwordx4 v[0:1], v[4:7], off offset:16
	s_branch .LBB0_419

.LBB0_612:
	s_or_b64 exec, exec, s[36:37]
	v_add_u32_e32 v0, v166, v163
	s_waitcnt vmcnt(3)
	ds_write_b16 v0, v152
	s_waitcnt vmcnt(2)
	ds_write_b16 v184, v145
	s_waitcnt lgkmcnt(0)
	s_barrier
	global_load_dword v198, v[66:67], off
	global_load_dword v199, v[68:69], off
	global_load_dword v200, v[70:71], off
	global_load_dword v201, v[72:73], off
	global_load_dword v202, v[74:75], off
	global_load_dword v203, v[76:77], off
	global_load_dword v204, v[78:79], off
	global_load_dword v205, v[84:85], off
	global_load_dword v206, v[86:87], off
	global_load_dword v207, v[88:89], off
	global_load_dword v216, v[90:91], off
	global_load_dword v217, v[92:93], off
	global_load_dword v218, v[94:95], off
	global_load_dword v219, v[96:97], off
	global_load_dword v220, v[98:99], off
	global_load_dword v221, v[100:101], off
	global_load_dword v223, v[102:103], off
	global_load_dword v224, v[104:105], off
	global_load_dword v225, v[106:107], off
	global_load_dword v229, v[108:109], off
	global_load_dword v230, v[110:111], off
	global_load_dword v232, v[112:113], off
	global_load_dword v239, v[114:115], off
	global_load_dword v240, v[116:117], off
	global_load_dword v241, v[118:119], off
	global_load_dword v242, v[120:121], off
	global_load_dword v243, v[122:123], off
	global_load_dword v244, v[124:125], off
	global_load_dword v245, v[126:127], off
	global_load_dword v246, v[128:129], off
	global_load_dword v247, v[130:131], off
	v_mov_b32_e32 v32, 0x80
	v_med3_i32 v33, v178, 0, v32
	v_add_u32_e32 v34, 0xffffff80, v178
	v_med3_i32 v34, v34, 0, v32
	v_lshlrev_b32_e32 v33, 2, v33
	v_lshlrev_b32_e32 v34, 2, v34
	v_or_b32_e32 v33, s89, v33
	v_or_b32_e32 v34, s89, v34
	v_lshlrev_b32_e32 v33, 2, v33
	v_lshlrev_b32_e32 v34, 2, v34
	global_load_dword v28, v33, s[58:59]
	global_load_dword v29, v33, s[58:59] offset:4
	global_load_dword v30, v34, s[58:59]
	global_load_dword v31, v34, s[58:59] offset:4
	v_add_u32_e32 v0, s89, v157
	v_lshl_add_u32 v3, v0, 10, v53
	ds_read2st64_b32 v[210:211], v3 offset1:4
	ds_read2st64_b32 v[248:249], v3 offset0:8 offset1:12
	ds_read_b32 v195, v3 offset:30720
	s_waitcnt vmcnt(0)
	s_waitcnt lgkmcnt(2)
	v_fmac_f32_e32 v143, v198, v210
	v_fmac_f32_e32 v143, v199, v211
	ds_read2st64_b32 v[210:211], v3 offset0:16 offset1:20
	s_waitcnt lgkmcnt(2)
	v_fmac_f32_e32 v143, v200, v248
	v_fmac_f32_e32 v143, v201, v249
	ds_read2st64_b32 v[248:249], v3 offset0:24 offset1:28
	s_waitcnt lgkmcnt(1)
	v_fmac_f32_e32 v143, v202, v210
	v_fmac_f32_e32 v143, v203, v211
	ds_read2st64_b32 v[210:211], v3 offset0:32 offset1:36
	s_waitcnt lgkmcnt(1)
	v_fmac_f32_e32 v143, v204, v248
	v_fmac_f32_e32 v143, v205, v249
	ds_read2st64_b32 v[248:249], v3 offset0:40 offset1:44
	s_waitcnt lgkmcnt(1)
	v_fmac_f32_e32 v143, v206, v210
	v_fmac_f32_e32 v143, v207, v211
	ds_read2st64_b32 v[210:211], v3 offset0:48 offset1:52
	s_waitcnt lgkmcnt(1)
	v_fmac_f32_e32 v143, v216, v248
	v_fmac_f32_e32 v143, v217, v249
	ds_read2st64_b32 v[248:249], v3 offset0:56 offset1:60
	s_waitcnt lgkmcnt(1)
	v_fmac_f32_e32 v143, v218, v210
	v_fmac_f32_e32 v143, v219, v211
	ds_read2st64_b32 v[210:211], v3 offset0:64 offset1:68
	s_waitcnt lgkmcnt(1)
	v_fmac_f32_e32 v143, v220, v248
	v_fmac_f32_e32 v143, v221, v249
	ds_read2st64_b32 v[248:249], v3 offset0:72 offset1:76
	s_waitcnt lgkmcnt(1)
	v_fmac_f32_e32 v143, v223, v210
	v_fmac_f32_e32 v143, v224, v211
	ds_read2st64_b32 v[210:211], v3 offset0:80 offset1:84
	s_waitcnt lgkmcnt(1)
	v_fmac_f32_e32 v143, v225, v248
	v_fmac_f32_e32 v143, v229, v249
	ds_read2st64_b32 v[248:249], v3 offset0:88 offset1:92
	s_waitcnt lgkmcnt(1)
	v_fmac_f32_e32 v143, v230, v210
	v_fmac_f32_e32 v143, v232, v211
	ds_read2st64_b32 v[210:211], v3 offset0:96 offset1:100
	s_waitcnt lgkmcnt(1)
	v_fmac_f32_e32 v143, v239, v248
	v_fmac_f32_e32 v143, v240, v249
	ds_read2st64_b32 v[248:249], v3 offset0:104 offset1:108
	s_waitcnt lgkmcnt(1)
	v_fmac_f32_e32 v143, v241, v210
	v_fmac_f32_e32 v143, v242, v211
	ds_read2st64_b32 v[210:211], v3 offset0:112 offset1:116
	s_waitcnt lgkmcnt(1)
	v_fmac_f32_e32 v143, v243, v248
	v_fmac_f32_e32 v143, v244, v249
	s_waitcnt lgkmcnt(0)
	v_fmac_f32_e32 v143, v245, v210
	v_fmac_f32_e32 v143, v246, v211
	s_waitcnt lgkmcnt(0)
	v_fmac_f32_e32 v143, v247, v195
	ds_write_b32 v3, v143 offset:34816
	s_and_saveexec_b64 s[36:37], s[18:19]
	s_cbranch_execz .LBB0_615
	s_add_u32 s34, s83, s34
	s_addc_u32 s35, s84, s35
	s_mul_i32 s38, s71, 0x3c00
	s_add_u32 s34, s34, s38
	v_cndmask_b32_e64 v0, 0, 1, s[64:65]
	s_movk_i32 s38, 0x3c00
	v_mul_lo_u32 v0, v0, s38
	s_addc_u32 s35, s35, 0
	v_add_u32_e32 v2, v155, v0
	s_mov_b64 s[38:39], 0
	v_mov_b32_e32 v0, v54
	v_mov_b32_e32 v3, v177

.LBB0_619:
	ds_read_b128 v[6:9], v186
	v_add_u32_e32 v5, v2, v168
	ds_read_b128 v[10:13], v5 offset:38912
	v_cmp_ge_i32_e64 s[34:35], v3, v63
	v_cmp_le_i32_e64 s[36:37], v3, v169
	s_and_b64 s[34:35], s[34:35], s[36:37]
	s_add_i32 s39, s39, 8
	v_add_u32_e32 v3, 0x80, v3
	v_add_u32_e32 v2, 0x4800, v2
	s_waitcnt lgkmcnt(0)
	v_mfma_f32_16x16x32_bf16 v[6:9], v[6:9], v[10:13], 0
	ds_read_b128 v[10:13], v186 offset:64
	ds_read_b128 v[14:17], v5 offset:38976
	s_waitcnt lgkmcnt(0)
	v_mfma_f32_16x16x32_bf16 v[6:9], v[10:13], v[14:17], v[6:9]
	v_add_u32_e32 v4, 0xffffff80, v4
	s_cmp_lt_i32 s39, 1
	s_nop 5
	v_cndmask_b32_e32 v6, v8, v6, vcc
	v_mov_b32_e32 v8, v28
	v_fmac_f32_e32 v8, 0x3e000000, v6
	v_cndmask_b32_e64 v6, v228, v8, s[34:35]
	ds_write_b32 v0, v6
	v_cndmask_b32_e32 v6, v9, v7, vcc
	v_mov_b32_e32 v5, v29
	v_add_u32_e32 v0, 0x200, v0
	v_fmac_f32_e32 v5, 0x3e000000, v6
	v_cndmask_b32_e64 v5, v228, v5, s[34:35]
	ds_write_b32 v1, v5
	v_add_u32_e32 v1, 0x200, v1
	v_mov_b32_e32 v28, v30
	v_mov_b32_e32 v29, v31
	s_cbranch_scc1 .LBB0_619
